# attention outputs: permlane32_swap pairs and dwordx4 stores (memory attention 16->8, sliding window 8->4 per lane)
# speedup vs baseline: 1.0126x; 1.0126x over previous
.LBB0_486:
	ds_bpermute_b32 v32, v80, v65
	v_sub_f32_e32 v33, v90, v38
	v_mul_f32_e32 v33, 0x3fb8aa3b, v33
	v_exp_f32_e32 v33, v33
	s_add_i32 s39, s39, 1
	s_waitcnt lgkmcnt(0)
	v_add_f32_e32 v32, v65, v32
	v_mov_b32_e32 v65, v137
	v_add_f32_e32 v32, v33, v32
	v_div_scale_f32 v33, s[0:1], v32, v32, 1.0
	v_rcp_f32_e32 v34, v33
	v_div_scale_f32 v35, vcc, 1.0, v32, 1.0
	v_readlane_b32 s0, v243, 54
	v_fma_f32 v36, -v33, v34, 1.0
	v_fmac_f32_e32 v34, v36, v34
	v_mul_f32_e32 v36, v35, v34
	v_fma_f32 v37, -v33, v36, v35
	v_fmac_f32_e32 v36, v37, v34
	v_fma_f32 v33, -v33, v36, v35
	v_div_fmas_f32 v33, v33, v34, v36
	v_div_fixup_f32 v32, v33, v32, 1.0
	v_readlane_b32 s1, v243, 55
	v_pk_mul_f32 v[0:1], v[0:1], v[32:33] op_sel_hi:[1,0]
	v_pk_mul_f32 v[2:3], v[2:3], v[32:33] op_sel_hi:[1,0]
	v_pk_mul_f32 v[4:5], v[4:5], v[32:33] op_sel_hi:[1,0]
	v_pk_mul_f32 v[6:7], v[6:7], v[32:33] op_sel_hi:[1,0]
	v_pk_mul_f32 v[8:9], v[8:9], v[32:33] op_sel_hi:[1,0]
	v_pk_mul_f32 v[10:11], v[10:11], v[32:33] op_sel_hi:[1,0]
	v_pk_mul_f32 v[12:13], v[12:13], v[32:33] op_sel_hi:[1,0]
	v_pk_mul_f32 v[14:15], v[14:15], v[32:33] op_sel_hi:[1,0]
	v_pk_mul_f32 v[16:17], v[16:17], v[32:33] op_sel_hi:[1,0]
	v_pk_mul_f32 v[18:19], v[18:19], v[32:33] op_sel_hi:[1,0]
	v_pk_mul_f32 v[20:21], v[20:21], v[32:33] op_sel_hi:[1,0]
	v_pk_mul_f32 v[22:23], v[22:23], v[32:33] op_sel_hi:[1,0]
	v_pk_mul_f32 v[24:25], v[24:25], v[32:33] op_sel_hi:[1,0]
	v_pk_mul_f32 v[26:27], v[26:27], v[32:33] op_sel_hi:[1,0]
	v_pk_mul_f32 v[28:29], v[28:29], v[32:33] op_sel_hi:[1,0]
	v_pk_mul_f32 v[30:31], v[30:31], v[32:33] op_sel_hi:[1,0]
	v_lshl_add_u64 v[34:35], v[66:67], 1, s[0:1]
	v_lshlrev_b32_e32 v36, 1, v64
	v_lshl_add_u64 v[34:35], v[68:69], 1, v[34:35]
	v_mov_b32_e32 v37, 0
	v_lshl_add_u64 v[34:35], v[34:35], 0, v[36:37]
	v_cvt_pk_bf16_f32 v16, v16, v17
	v_cvt_pk_bf16_f32 v17, v18, v19
	v_cvt_pk_bf16_f32 v18, v20, v21
	v_cvt_pk_bf16_f32 v19, v22, v23
	v_cvt_pk_bf16_f32 v24, v24, v25
	v_cvt_pk_bf16_f32 v25, v26, v27
	v_cvt_pk_bf16_f32 v26, v28, v29
	v_cvt_pk_bf16_f32 v27, v30, v31
	s_nop 1
	v_permlane32_swap_b32_e32 v16, v18
	v_permlane32_swap_b32_e32 v17, v19
	v_permlane32_swap_b32_e32 v24, v26
	v_permlane32_swap_b32_e32 v25, v27
	global_store_dwordx4 v[34:35], v[16:19], off
	global_store_dwordx4 v[34:35], v[24:27], off offset:32
	v_cvt_pk_bf16_f32 v0, v0, v1
	v_cvt_pk_bf16_f32 v1, v2, v3
	v_cvt_pk_bf16_f32 v2, v4, v5
	v_cvt_pk_bf16_f32 v3, v6, v7
	v_cvt_pk_bf16_f32 v8, v8, v9
	v_cvt_pk_bf16_f32 v9, v10, v11
	v_cvt_pk_bf16_f32 v10, v12, v13
	v_cvt_pk_bf16_f32 v11, v14, v15
	s_nop 1
	v_permlane32_swap_b32_e32 v0, v2
	v_permlane32_swap_b32_e32 v1, v3
	v_permlane32_swap_b32_e32 v8, v10
	v_permlane32_swap_b32_e32 v9, v11
	global_store_dwordx4 v[34:35], v[0:3], off offset:64
	global_store_dwordx4 v[34:35], v[8:11], off offset:96
	v_cmp_eq_u32_e32 vcc, s39, v73
	s_nop 1
	s_or_b64 s[30:31], vcc, s[30:31]
	s_andn2_b64 exec, exec, s[30:31]
	s_cbranch_execz .LBB0_524

.LBB0_555:
	v_add_u32_e32 v64, s28, v130
	ds_read_b128 v[64:67], v64
	v_add_u32_e32 v139, s28, v129
	ds_read_b128 v[140:143], v139
	v_add_u32_e32 v138, s28, v128
	v_add_u32_e32 v136, s28, v127
	v_add_u32_e32 v135, s28, v126
	v_add_u32_e32 v134, s28, v125
	v_add_u32_e32 v114, s28, v124
	v_add_u32_e32 v112, s28, v123
	s_waitcnt vmcnt(7) lgkmcnt(1)
	v_mfma_f32_32x32x16_bf16 v[64:79], v[64:67], v[80:83], 0
	v_mov_b32_e32 v118, v132
	s_addk_i32 s28, 0x2000
	s_waitcnt vmcnt(6) lgkmcnt(0)
	v_mfma_f32_32x32x16_bf16 v[64:79], v[140:143], v[84:87], v[64:79]
	ds_read_b128 v[138:141], v138
	s_cmp_lg_u32 s28, 0x10000
	s_waitcnt vmcnt(5) lgkmcnt(0)
	v_mfma_f32_32x32x16_bf16 v[64:79], v[138:141], v[88:91], v[64:79]
	ds_read_b128 v[138:141], v136
	s_waitcnt vmcnt(4) lgkmcnt(0)
	v_mfma_f32_32x32x16_bf16 v[64:79], v[138:141], v[92:95], v[64:79]
	ds_read_b128 v[138:141], v135
	s_waitcnt vmcnt(3) lgkmcnt(0)
	v_mfma_f32_32x32x16_bf16 v[64:79], v[138:141], v[96:99], v[64:79]
	ds_read_b128 v[138:141], v134
	s_waitcnt vmcnt(2) lgkmcnt(0)
	v_mfma_f32_32x32x16_bf16 v[64:79], v[138:141], v[100:103], v[64:79]
	ds_read_b128 v[138:141], v114
	ds_read_b128 v[142:145], v112
	s_waitcnt vmcnt(1) lgkmcnt(1)
	v_mfma_f32_32x32x16_bf16 v[64:79], v[138:141], v[104:107], v[64:79]
	ds_read_b64_tr_b16 v[138:139], v174
	ds_read_b64_tr_b16 v[140:141], v175
	ds_read_b64_tr_b16 v[148:149], v176
	ds_read_b64_tr_b16 v[150:151], v177
	ds_read_b64_tr_b16 v[112:113], v174 offset:2048
	ds_read_b64_tr_b16 v[114:115], v175 offset:2048
	s_waitcnt vmcnt(0) lgkmcnt(6)
	v_mfma_f32_32x32x16_bf16 v[64:79], v[142:145], v[108:111], v[64:79]
	s_nop 11
	v_mul_f32_e32 v132, 0x3db504f3, v64
	v_mul_f32_e32 v136, 0x3db504f3, v65
	v_mul_f32_e32 v142, 0x3db504f3, v66
	v_mul_f32_e32 v143, 0x3db504f3, v67
	v_max3_f32 v132, v132, s33, v136
	v_mul_f32_e32 v144, 0x3db504f3, v68
	v_mul_f32_e32 v145, 0x3db504f3, v69
	v_max3_f32 v132, v132, v142, v143
	v_mul_f32_e32 v146, 0x3db504f3, v70
	v_mul_f32_e32 v152, 0x3db504f3, v71
	v_max3_f32 v132, v132, v144, v145
	v_mul_f32_e32 v153, 0x3db504f3, v72
	v_mul_f32_e32 v154, 0x3db504f3, v73
	v_max3_f32 v132, v132, v146, v152
	v_mul_f32_e32 v155, 0x3db504f3, v74
	v_mul_f32_e32 v156, 0x3db504f3, v75
	v_max3_f32 v132, v132, v153, v154
	v_mul_f32_e32 v157, 0x3db504f3, v76
	v_mul_f32_e32 v158, 0x3db504f3, v77
	v_max3_f32 v132, v132, v155, v156
	v_mul_f32_e32 v159, 0x3db504f3, v78
	v_mul_f32_e32 v160, 0x3db504f3, v79
	v_max3_f32 v132, v132, v157, v158
	v_max3_f32 v132, v132, v159, v160
	ds_bpermute_b32 v136, v121, v132
	s_waitcnt lgkmcnt(5)
	v_mov_b32_e32 v142, v138
	v_mov_b32_e32 v143, v139
	s_waitcnt lgkmcnt(1)
	v_mov_b32_e32 v144, v112
	v_mov_b32_e32 v145, v113
	s_waitcnt lgkmcnt(0)
	v_max3_f32 v132, v118, v132, v136
	v_fma_f32 v136, v64, s22, -v132
	v_fma_f32 v146, v65, s22, -v132
	v_fma_f32 v152, v66, s22, -v132
	v_fma_f32 v153, v67, s22, -v132
	v_fma_f32 v154, v68, s22, -v132
	v_fma_f32 v155, v69, s22, -v132
	v_fma_f32 v156, v70, s22, -v132
	v_fma_f32 v157, v71, s22, -v132
	ds_read_b64_tr_b16 v[68:69], v176 offset:2048
	ds_read_b64_tr_b16 v[70:71], v177 offset:2048
	ds_read_b64_tr_b16 v[64:65], v174 offset:4096
	ds_read_b64_tr_b16 v[66:67], v175 offset:4096
	v_fma_f32 v166, v76, s22, -v132
	v_sub_f32_e32 v76, v118, v132
	v_mul_f32_e32 v76, 0x3fb8aa3b, v76
	v_mul_f32_e32 v118, 0x3fb8aa3b, v153
	v_fma_f32 v158, v72, s22, -v132
	v_fma_f32 v159, v73, s22, -v132
	v_fma_f32 v160, v74, s22, -v132
	v_fma_f32 v161, v75, s22, -v132
	v_mov_b32_e32 v72, v148
	v_mov_b32_e32 v73, v149
	s_waitcnt lgkmcnt(2)
	v_mov_b32_e32 v74, v68
	v_mov_b32_e32 v75, v69
	v_mov_b32_e32 v68, v150
	v_exp_f32_e32 v150, v118
	v_exp_f32_e32 v118, v76
	v_fma_f32 v167, v77, s22, -v132
	v_fma_f32 v168, v78, s22, -v132
	v_fma_f32 v169, v79, s22, -v132
	v_mov_b32_e32 v112, v140
	v_mov_b32_e32 v113, v141
	v_mul_f32_e32 v77, 0x3fb8aa3b, v136
	v_mul_f32_e32 v78, 0x3fb8aa3b, v146
	v_mul_f32_e32 v79, 0x3fb8aa3b, v152
	v_mul_f32_e32 v134, 0x3fb8aa3b, v154
	v_mul_f32_e32 v136, 0x3fb8aa3b, v155
	v_mul_f32_e32 v138, 0x3fb8aa3b, v156
	v_mul_f32_e32 v139, 0x3fb8aa3b, v157
	v_pk_mul_f32 v[46:47], v[46:47], v[118:119] op_sel_hi:[1,0]
	v_pk_mul_f32 v[44:45], v[44:45], v[118:119] op_sel_hi:[1,0]
	v_pk_mul_f32 v[42:43], v[42:43], v[118:119] op_sel_hi:[1,0]
	v_pk_mul_f32 v[40:41], v[40:41], v[118:119] op_sel_hi:[1,0]
	v_pk_mul_f32 v[38:39], v[38:39], v[118:119] op_sel_hi:[1,0]
	v_pk_mul_f32 v[36:37], v[36:37], v[118:119] op_sel_hi:[1,0]
	v_pk_mul_f32 v[34:35], v[34:35], v[118:119] op_sel_hi:[1,0]
	v_pk_mul_f32 v[32:33], v[32:33], v[118:119] op_sel_hi:[1,0]
	v_pk_mul_f32 v[14:15], v[14:15], v[118:119] op_sel_hi:[1,0]
	v_pk_mul_f32 v[12:13], v[12:13], v[118:119] op_sel_hi:[1,0]
	v_pk_mul_f32 v[10:11], v[10:11], v[118:119] op_sel_hi:[1,0]
	v_pk_mul_f32 v[8:9], v[8:9], v[118:119] op_sel_hi:[1,0]
	v_pk_mul_f32 v[6:7], v[6:7], v[118:119] op_sel_hi:[1,0]
	v_pk_mul_f32 v[4:5], v[4:5], v[118:119] op_sel_hi:[1,0]
	v_pk_mul_f32 v[2:3], v[2:3], v[118:119] op_sel_hi:[1,0]
	v_pk_mul_f32 v[0:1], v[0:1], v[118:119] op_sel_hi:[1,0]
	v_mov_b32_e32 v69, v151
	v_exp_f32_e32 v146, v77
	v_exp_f32_e32 v148, v78
	v_exp_f32_e32 v149, v79
	v_exp_f32_e32 v134, v134
	v_exp_f32_e32 v136, v136
	v_exp_f32_e32 v151, v138
	v_exp_f32_e32 v152, v139
	v_cvt_pk_bf16_f32 v76, v146, v148
	v_cvt_pk_bf16_f32 v77, v149, v150
	v_cvt_pk_bf16_f32 v78, v134, v136
	v_cvt_pk_bf16_f32 v79, v151, v152
	v_pk_mul_f32 v[30:31], v[30:31], v[118:119] op_sel_hi:[1,0]
	v_mfma_f32_32x32x16_bf16 v[32:47], v[142:145], v[76:79], v[32:47]
	ds_read_b64_tr_b16 v[138:139], v174 offset:6144
	ds_read_b64_tr_b16 v[140:141], v175 offset:6144
	ds_read_b64_tr_b16 v[142:143], v176 offset:4096
	ds_read_b64_tr_b16 v[144:145], v177 offset:4096
	v_mul_f32_e64 v28, v28, v118
	v_mul_f32_e64 v29, v29, v118
	v_mul_f32_e64 v26, v26, v118
	v_mul_f32_e64 v27, v27, v118
	v_pk_mul_f32 v[24:25], v[24:25], v[118:119] op_sel_hi:[1,0]
	v_pk_mul_f32 v[22:23], v[22:23], v[118:119] op_sel_hi:[1,0]
	v_pk_mul_f32 v[20:21], v[20:21], v[118:119] op_sel_hi:[1,0]
	v_pk_mul_f32 v[18:19], v[18:19], v[118:119] op_sel_hi:[1,0]
	v_mfma_f32_32x32x16_bf16 v[0:15], v[72:75], v[76:79], v[0:15]
	ds_read_b64_tr_b16 v[72:73], v176 offset:6144
	ds_read_b64_tr_b16 v[74:75], v177 offset:6144
	v_mul_f32_e64 v16, v16, v118
	v_mul_f32_e64 v17, v17, v118
	v_mul_f32_e64 v62, v62, v118
	v_mul_f32_e64 v63, v63, v118
	v_pk_mul_f32 v[60:61], v[60:61], v[118:119] op_sel_hi:[1,0]
	v_pk_mul_f32 v[58:59], v[58:59], v[118:119] op_sel_hi:[1,0]
	v_pk_mul_f32 v[56:57], v[56:57], v[118:119] op_sel_hi:[1,0]
	v_pk_mul_f32 v[54:55], v[54:55], v[118:119] op_sel_hi:[1,0]
	v_mfma_f32_32x32x16_bf16 v[16:31], v[112:115], v[76:79], v[16:31]
	s_waitcnt lgkmcnt(6)
	v_mov_b32_e32 v112, v64
	v_mov_b32_e32 v113, v65
	s_waitcnt lgkmcnt(4)
	v_mov_b32_e32 v114, v138
	v_mov_b32_e32 v115, v139
	v_mul_f32_e32 v64, 0x3fb8aa3b, v158
	v_mul_f32_e32 v65, 0x3fb8aa3b, v159
	v_mul_f32_e32 v138, 0x3fb8aa3b, v161
	v_mul_f32_e32 v139, 0x3fb8aa3b, v166
	v_exp_f32_e32 v156, v64
	v_exp_f32_e32 v157, v65
	v_exp_f32_e32 v158, v138
	v_exp_f32_e32 v159, v139
	v_mov_b32_e32 v138, v66
	v_mov_b32_e32 v139, v67
	s_waitcnt lgkmcnt(2)
	v_mov_b32_e32 v64, v142
	v_mov_b32_e32 v65, v143
	s_waitcnt lgkmcnt(0)
	v_mov_b32_e32 v66, v72
	v_mov_b32_e32 v67, v73
	v_pk_mul_f32 v[52:53], v[52:53], v[118:119] op_sel_hi:[1,0]
	v_pk_mul_f32 v[50:51], v[50:51], v[118:119] op_sel_hi:[1,0]
	v_pk_mul_f32 v[48:49], v[48:49], v[118:119] op_sel_hi:[1,0]
	v_fmac_f32_e32 v146, v131, v118
	v_mul_f32_e32 v135, 0x3fb8aa3b, v160
	v_mfma_f32_32x32x16_bf16 v[48:63], v[68:71], v[76:79], v[48:63]
	v_mul_f32_e32 v153, 0x3fb8aa3b, v167
	v_mul_f32_e32 v154, 0x3fb8aa3b, v168
	v_mul_f32_e32 v155, 0x3fb8aa3b, v169
	v_add_f32_e32 v79, v148, v146
	v_exp_f32_e32 v135, v135
	v_exp_f32_e32 v76, v153
	v_exp_f32_e32 v77, v154
	v_exp_f32_e32 v78, v155
	v_cvt_pk_bf16_f32 v68, v156, v157
	v_cvt_pk_bf16_f32 v69, v135, v158
	v_cvt_pk_bf16_f32 v70, v159, v76
	v_cvt_pk_bf16_f32 v71, v77, v78
	v_mov_b32_e32 v72, v144
	v_mfma_f32_32x32x16_bf16 v[0:15], v[64:67], v[68:71], v[0:15]
	v_add_f32_e32 v64, v149, v79
	v_mov_b32_e32 v73, v145
	v_add_f32_e32 v64, v150, v64
	v_add_f32_e32 v64, v134, v64
	v_add_f32_e32 v64, v136, v64
	v_add_f32_e32 v64, v151, v64
	v_add_f32_e32 v64, v152, v64
	v_mfma_f32_32x32x16_bf16 v[32:47], v[112:115], v[68:71], v[32:47]
	v_add_f32_e32 v64, v156, v64
	v_add_f32_e32 v64, v157, v64
	v_add_f32_e32 v64, v135, v64
	v_add_f32_e32 v64, v158, v64
	v_add_f32_e32 v64, v159, v64
	v_add_f32_e32 v64, v76, v64
	v_add_f32_e32 v64, v77, v64
	v_mfma_f32_32x32x16_bf16 v[16:31], v[138:141], v[68:71], v[16:31]
	v_add_f32_e32 v131, v78, v64
	v_mfma_f32_32x32x16_bf16 v[48:63], v[72:75], v[68:71], v[48:63]
	v_add_u32_e32 v174, 0x2000, v174
	v_add_u32_e32 v175, 0x2000, v175
	v_add_u32_e32 v176, 0x2000, v176
	v_add_u32_e32 v177, 0x2000, v177
	s_cbranch_scc1 .LBB0_555
	ds_bpermute_b32 v64, v121, v131
	v_cmp_gt_u32_e32 vcc, 8, v119
	s_or_b64 s[0:1], s[0:1], vcc
	s_and_b64 exec, exec, s[0:1]
	s_cbranch_execz .LBB0_454
	v_sub_f32_e32 v65, 0xff800000, v132
	v_mul_f32_e32 v65, 0x3fb8aa3b, v65
	v_exp_f32_e32 v65, v65
	s_waitcnt lgkmcnt(0)
	v_add_f32_e32 v64, v131, v64
	s_lshl_b32 s34, s38, 1
	v_add_f32_e32 v64, v65, v64
	v_div_scale_f32 v65, s[0:1], v64, v64, 1.0
	v_rcp_f32_e32 v66, v65
	v_div_scale_f32 v67, vcc, 1.0, v64, 1.0
	v_readlane_b32 s0, v243, 54
	v_fma_f32 v68, -v65, v66, 1.0
	v_fmac_f32_e32 v66, v68, v66
	v_mul_f32_e32 v68, v67, v66
	v_fma_f32 v69, -v65, v68, v67
	v_fmac_f32_e32 v68, v69, v66
	v_fma_f32 v65, -v65, v68, v67
	v_div_fmas_f32 v65, v65, v66, v68
	v_div_fixup_f32 v64, v65, v64, 1.0
	v_readlane_b32 s1, v243, 55
	v_pk_mul_f32 v[0:1], v[0:1], v[64:65] op_sel_hi:[1,0]
	v_pk_mul_f32 v[2:3], v[2:3], v[64:65] op_sel_hi:[1,0]
	v_pk_mul_f32 v[4:5], v[4:5], v[64:65] op_sel_hi:[1,0]
	v_pk_mul_f32 v[6:7], v[6:7], v[64:65] op_sel_hi:[1,0]
	v_pk_mul_f32 v[8:9], v[8:9], v[64:65] op_sel_hi:[1,0]
	v_pk_mul_f32 v[10:11], v[10:11], v[64:65] op_sel_hi:[1,0]
	v_pk_mul_f32 v[12:13], v[12:13], v[64:65] op_sel_hi:[1,0]
	v_pk_mul_f32 v[14:15], v[14:15], v[64:65] op_sel_hi:[1,0]
	v_pk_mul_f32 v[16:17], v[16:17], v[64:65] op_sel_hi:[1,0]
	v_pk_mul_f32 v[18:19], v[18:19], v[64:65] op_sel_hi:[1,0]
	v_pk_mul_f32 v[20:21], v[20:21], v[64:65] op_sel_hi:[1,0]
	v_pk_mul_f32 v[22:23], v[22:23], v[64:65] op_sel_hi:[1,0]
	v_pk_mul_f32 v[24:25], v[24:25], v[64:65] op_sel_hi:[1,0]
	v_pk_mul_f32 v[26:27], v[26:27], v[64:65] op_sel_hi:[1,0]
	v_pk_mul_f32 v[28:29], v[28:29], v[64:65] op_sel_hi:[1,0]
	v_pk_mul_f32 v[30:31], v[30:31], v[64:65] op_sel_hi:[1,0]
	v_pk_mul_f32 v[32:33], v[32:33], v[64:65] op_sel_hi:[1,0]
	v_pk_mul_f32 v[34:35], v[34:35], v[64:65] op_sel_hi:[1,0]
	v_pk_mul_f32 v[36:37], v[36:37], v[64:65] op_sel_hi:[1,0]
	v_pk_mul_f32 v[38:39], v[38:39], v[64:65] op_sel_hi:[1,0]
	v_pk_mul_f32 v[40:41], v[40:41], v[64:65] op_sel_hi:[1,0]
	v_pk_mul_f32 v[42:43], v[42:43], v[64:65] op_sel_hi:[1,0]
	v_pk_mul_f32 v[44:45], v[44:45], v[64:65] op_sel_hi:[1,0]
	v_pk_mul_f32 v[46:47], v[46:47], v[64:65] op_sel_hi:[1,0]
	v_pk_mul_f32 v[48:49], v[48:49], v[64:65] op_sel_hi:[1,0]
	v_pk_mul_f32 v[50:51], v[50:51], v[64:65] op_sel_hi:[1,0]
	v_pk_mul_f32 v[52:53], v[52:53], v[64:65] op_sel_hi:[1,0]
	v_pk_mul_f32 v[54:55], v[54:55], v[64:65] op_sel_hi:[1,0]
	v_pk_mul_f32 v[56:57], v[56:57], v[64:65] op_sel_hi:[1,0]
	v_pk_mul_f32 v[58:59], v[58:59], v[64:65] op_sel_hi:[1,0]
	v_pk_mul_f32 v[60:61], v[60:61], v[64:65] op_sel_hi:[1,0]
	v_pk_mul_f32 v[62:63], v[62:63], v[64:65] op_sel_hi:[1,0]
	v_mov_b64_e32 v[66:67], s[0:1]
	s_movk_i32 s0, 0xc00
	v_mad_i64_i32 v[66:67], s[0:1], v116, s0, v[66:67]
	v_lshrrev_b32_e32 v68, 1, v117
	v_lshl_add_u64 v[66:67], v[66:67], 0, s[34:35]
	v_and_b32_e32 v136, 16, v68
	v_lshl_add_u64 v[66:67], v[66:67], 0, v[136:137]
	v_cvt_pk_bf16_f32 v32, v32, v33
	v_cvt_pk_bf16_f32 v33, v34, v35
	v_cvt_pk_bf16_f32 v34, v36, v37
	v_cvt_pk_bf16_f32 v35, v38, v39
	v_cvt_pk_bf16_f32 v40, v40, v41
	v_cvt_pk_bf16_f32 v41, v42, v43
	v_cvt_pk_bf16_f32 v42, v44, v45
	v_cvt_pk_bf16_f32 v43, v46, v47
	s_nop 1
	v_permlane32_swap_b32_e32 v32, v34
	v_permlane32_swap_b32_e32 v33, v35
	v_permlane32_swap_b32_e32 v40, v42
	v_permlane32_swap_b32_e32 v41, v43
	global_store_dwordx4 v[66:67], v[32:35], off offset:2048
	global_store_dwordx4 v[66:67], v[40:43], off offset:2080
	v_cvt_pk_bf16_f32 v16, v16, v17
	v_cvt_pk_bf16_f32 v17, v18, v19
	v_cvt_pk_bf16_f32 v18, v20, v21
	v_cvt_pk_bf16_f32 v19, v22, v23
	v_cvt_pk_bf16_f32 v24, v24, v25
	v_cvt_pk_bf16_f32 v25, v26, v27
	v_cvt_pk_bf16_f32 v26, v28, v29
	v_cvt_pk_bf16_f32 v27, v30, v31
	s_nop 1
	v_permlane32_swap_b32_e32 v16, v18
	v_permlane32_swap_b32_e32 v17, v19
	v_permlane32_swap_b32_e32 v24, v26
	v_permlane32_swap_b32_e32 v25, v27
	global_store_dwordx4 v[66:67], v[16:19], off offset:2112
	global_store_dwordx4 v[66:67], v[24:27], off offset:2144
	v_cvt_pk_bf16_f32 v0, v0, v1
	v_cvt_pk_bf16_f32 v1, v2, v3
	v_cvt_pk_bf16_f32 v2, v4, v5
	v_cvt_pk_bf16_f32 v3, v6, v7
	v_cvt_pk_bf16_f32 v8, v8, v9
	v_cvt_pk_bf16_f32 v9, v10, v11
	v_cvt_pk_bf16_f32 v10, v12, v13
	v_cvt_pk_bf16_f32 v11, v14, v15
	s_nop 1
	v_permlane32_swap_b32_e32 v0, v2
	v_permlane32_swap_b32_e32 v1, v3
	v_permlane32_swap_b32_e32 v8, v10
	v_permlane32_swap_b32_e32 v9, v11
	global_store_dwordx4 v[66:67], v[0:3], off offset:2176
	global_store_dwordx4 v[66:67], v[8:11], off offset:2208
	v_cvt_pk_bf16_f32 v48, v48, v49
	v_cvt_pk_bf16_f32 v49, v50, v51
	v_cvt_pk_bf16_f32 v50, v52, v53
	v_cvt_pk_bf16_f32 v51, v54, v55
	v_cvt_pk_bf16_f32 v56, v56, v57
	v_cvt_pk_bf16_f32 v57, v58, v59
	v_cvt_pk_bf16_f32 v58, v60, v61
	v_cvt_pk_bf16_f32 v59, v62, v63
	s_nop 1
	v_permlane32_swap_b32_e32 v48, v50
	v_permlane32_swap_b32_e32 v49, v51
	v_permlane32_swap_b32_e32 v56, v58
	v_permlane32_swap_b32_e32 v57, v59
	global_store_dwordx4 v[66:67], v[48:51], off offset:2240
	global_store_dwordx4 v[66:67], v[56:59], off offset:2272
	s_branch .LBB0_454
